# softmax running-max exchange via v_permlane16/32_swap instead of ds_bpermute on top of band-mask rewrite
# speedup vs baseline: 1.0000x; 1.0000x over previous
.Lam_done_0:
.LBB0_981:
	v_max_f32_e32 v148, v133, v133
	v_max_f32_e32 v149, v132, v132
	v_max_f32_e32 v148, v149, v148
	v_max_f32_e32 v149, v135, v135
	v_max_f32_e32 v152, v134, v134
	v_max_f32_e32 v149, v152, v149
	s_nop 0
	v_max_f32_e32 v152, v139, v139
	v_max_f32_e32 v153, v138, v138
	v_max_f32_e32 v152, v153, v152
	v_max3_f32 v152, v136, v137, v152
	v_max3_f32 v148, v148, v149, v152
	v_mov_b32_e32 v149, v148
	s_nop 1
	v_permlane16_swap_b32_e32 v148, v149
	s_waitcnt lgkmcnt(0)
	v_max_f32_e32 v149, v149, v149
	v_max_f32_e32 v148, v148, v149
	v_mov_b32_e32 v149, v148
	s_nop 1
	v_permlane32_swap_b32_e32 v148, v149
	s_waitcnt lgkmcnt(0)
	v_max3_f32 v181, v179, v148, v149
	v_cmp_neq_f32_e32 vcc, v181, v179
	s_cbranch_vccz .LBB0_983
	v_sub_f32_e32 v148, v179, v181
	v_exp_f32_e32 v184, v148
	s_nop 0
	v_mul_f32_e32 v147, v147, v184
	v_pk_mul_f32 v[98:99], v[98:99], v[184:185] op_sel_hi:[1,0]
	v_pk_mul_f32 v[96:97], v[96:97], v[184:185] op_sel_hi:[1,0]
	v_pk_mul_f32 v[94:95], v[94:95], v[184:185] op_sel_hi:[1,0]
	v_pk_mul_f32 v[92:93], v[92:93], v[184:185] op_sel_hi:[1,0]
	v_pk_mul_f32 v[78:79], v[78:79], v[184:185] op_sel_hi:[1,0]
	v_pk_mul_f32 v[76:77], v[76:77], v[184:185] op_sel_hi:[1,0]
	v_pk_mul_f32 v[66:67], v[66:67], v[184:185] op_sel_hi:[1,0]
	v_pk_mul_f32 v[64:65], v[64:65], v[184:185] op_sel_hi:[1,0]

.Lam_done_1:
.LBB0_985:
	s_nop 5
	v_max_f32_e32 v148, v133, v133
	v_max_f32_e32 v149, v132, v132
	v_max_f32_e32 v148, v149, v148
	v_max_f32_e32 v149, v135, v135
	v_max_f32_e32 v152, v134, v134
	v_max_f32_e32 v149, v152, v149
	v_max_f32_e32 v152, v139, v139
	v_max_f32_e32 v153, v138, v138
	v_max_f32_e32 v152, v153, v152
	v_max3_f32 v152, v136, v137, v152
	v_max3_f32 v148, v148, v149, v152
	v_mov_b32_e32 v149, v148
	s_nop 1
	v_permlane16_swap_b32_e32 v148, v149
	s_waitcnt lgkmcnt(0)
	v_max_f32_e32 v149, v149, v149
	v_max_f32_e32 v148, v148, v149
	v_mov_b32_e32 v149, v148
	s_nop 1
	v_permlane32_swap_b32_e32 v148, v149
	s_waitcnt lgkmcnt(0)
	v_max3_f32 v190, v178, v148, v149
	v_cmp_neq_f32_e32 vcc, v190, v178
	s_cbranch_vccz .LBB0_987
	v_sub_f32_e32 v148, v178, v190
	v_exp_f32_e32 v178, v148
	s_nop 0
	v_mul_f32_e32 v167, v167, v178
	v_pk_mul_f32 v[50:51], v[50:51], v[178:179] op_sel_hi:[1,0]
	v_pk_mul_f32 v[48:49], v[48:49], v[178:179] op_sel_hi:[1,0]
	v_pk_mul_f32 v[46:47], v[46:47], v[178:179] op_sel_hi:[1,0]
	v_pk_mul_f32 v[44:45], v[44:45], v[178:179] op_sel_hi:[1,0]
	v_pk_mul_f32 v[42:43], v[42:43], v[178:179] op_sel_hi:[1,0]
	v_pk_mul_f32 v[40:41], v[40:41], v[178:179] op_sel_hi:[1,0]
	v_pk_mul_f32 v[38:39], v[38:39], v[178:179] op_sel_hi:[1,0]
	v_pk_mul_f32 v[36:37], v[36:37], v[178:179] op_sel_hi:[1,0]

.Lam_done_2:
.LBB0_989:
	s_nop 5
	v_max_f32_e32 v148, v133, v133
	v_max_f32_e32 v149, v132, v132
	v_max_f32_e32 v148, v149, v148
	v_max_f32_e32 v149, v135, v135
	v_max_f32_e32 v152, v134, v134
	v_max_f32_e32 v149, v152, v149
	v_max_f32_e32 v152, v139, v139
	v_max_f32_e32 v153, v138, v138
	v_max_f32_e32 v152, v153, v152
	v_max3_f32 v152, v136, v137, v152
	v_max3_f32 v148, v148, v149, v152
	v_mov_b32_e32 v149, v148
	s_nop 1
	v_permlane16_swap_b32_e32 v148, v149
	s_waitcnt lgkmcnt(0)
	v_max_f32_e32 v149, v149, v149
	v_max_f32_e32 v148, v148, v149
	v_mov_b32_e32 v149, v148
	s_nop 1
	v_permlane32_swap_b32_e32 v148, v149
	s_waitcnt lgkmcnt(0)
	v_max3_f32 v191, v177, v148, v149
	v_cmp_neq_f32_e32 vcc, v191, v177
	s_cbranch_vccz .LBB0_991
	v_sub_f32_e32 v148, v177, v191
	v_exp_f32_e32 v200, v148
	s_nop 0
	v_mul_f32_e32 v145, v145, v200
	v_pk_mul_f32 v[34:35], v[34:35], v[200:201] op_sel_hi:[1,0]
	v_pk_mul_f32 v[32:33], v[32:33], v[200:201] op_sel_hi:[1,0]
	v_pk_mul_f32 v[30:31], v[30:31], v[200:201] op_sel_hi:[1,0]
	v_pk_mul_f32 v[28:29], v[28:29], v[200:201] op_sel_hi:[1,0]
	v_pk_mul_f32 v[26:27], v[26:27], v[200:201] op_sel_hi:[1,0]
	v_pk_mul_f32 v[24:25], v[24:25], v[200:201] op_sel_hi:[1,0]
	v_pk_mul_f32 v[22:23], v[22:23], v[200:201] op_sel_hi:[1,0]
	v_pk_mul_f32 v[20:21], v[20:21], v[200:201] op_sel_hi:[1,0]

.Lam_done_3:
.LBB0_993:
	s_nop 1
	v_max_f32_e32 v124, v121, v121
	v_max_f32_e32 v125, v120, v120
	v_max_f32_e32 v124, v125, v124
	v_max_f32_e32 v125, v123, v123
	v_max_f32_e32 v126, v122, v122
	v_max_f32_e32 v125, v126, v125
	v_max_f32_e32 v126, v119, v119
	v_max_f32_e32 v127, v118, v118
	v_max_f32_e32 v126, v127, v126
	v_max3_f32 v126, v116, v117, v126
	v_max3_f32 v124, v124, v125, v126
	v_mov_b32_e32 v125, v124
	s_nop 1
	v_permlane16_swap_b32_e32 v124, v125
	s_waitcnt lgkmcnt(0)
	v_max_f32_e32 v125, v125, v125
	v_max_f32_e32 v124, v124, v125
	v_mov_b32_e32 v125, v124
	s_nop 1
	v_permlane32_swap_b32_e32 v124, v125
	s_waitcnt lgkmcnt(0)
	v_max3_f32 v124, v176, v124, v125
	v_cmp_neq_f32_e32 vcc, v124, v176
	s_cbranch_vccz .LBB0_995
	v_sub_f32_e32 v125, v176, v124
	v_exp_f32_e32 v126, v125
	s_nop 0
	v_mul_f32_e32 v143, v143, v126
	v_pk_mul_f32 v[18:19], v[18:19], v[126:127] op_sel_hi:[1,0]
	v_pk_mul_f32 v[16:17], v[16:17], v[126:127] op_sel_hi:[1,0]
	v_pk_mul_f32 v[14:15], v[14:15], v[126:127] op_sel_hi:[1,0]
	v_pk_mul_f32 v[12:13], v[12:13], v[126:127] op_sel_hi:[1,0]
	v_pk_mul_f32 v[10:11], v[10:11], v[126:127] op_sel_hi:[1,0]
	v_pk_mul_f32 v[8:9], v[8:9], v[126:127] op_sel_hi:[1,0]
	v_pk_mul_f32 v[6:7], v[6:7], v[126:127] op_sel_hi:[1,0]
	v_pk_mul_f32 v[4:5], v[4:5], v[126:127] op_sel_hi:[1,0]
